# swiglu epilogues (P1, P6): packed f32 multiplies/adds split into scalar pairs (instruction selection in a VALU-bound section, bit-identical)
# baseline (speedup 1.0000x reference)
; __device__ __forceinline__ unsigned pk2(float lo, float hi) { unsigned r; asm volatile("v_cvt_pk_bf16_f32 %0, %1, %2" : "=v"(r) : "v"(lo), "v"(hi)); return r; }
; __device__ __forceinline__ f32x2 swiglu_pk(f32x2 g, f32x2 u, float rs) {
;     const f32x2 t = g * rs, s = t * (-1.44269504089f);
;     f32x2 e; e.x = __builtin_amdgcn_exp2f(s.x); e.y = __builtin_amdgcn_exp2f(s.y);
;     const f32x2 d = e + 1.0f; f32x2 r; r.x = __builtin_amdgcn_rcpf(d.x); r.y = __builtin_amdgcn_rcpf(d.y);
;     return (t * r) * (u * rs);
; }
;     __device__ __forceinline__ void operator()(const f32x4 (&acc)[2][2][4][2], const Unit& u, int wr, int wc, int fr, int fq) const {
;         const int row0 = u.pm * BM + wr * 64 + fr, col0 = u.pn * 128 + wc * 32 + 8 * fq;
;         float rsv[8];
; #pragma unroll
;         for (int i = 0; i < 8; ++i) rsv[i] = ss[row0 + (i >> 2) * HALF + (i & 3) * 16];
; #pragma unroll
;         for (int i = 0; i < 8; ++i) rsv[i] = __builtin_amdgcn_rsqf(rsv[i] * (1.0f / D) + EPS);
;         __builtin_amdgcn_sched_barrier(0);
; #pragma unroll
;         for (int ai = 0; ai < 2; ++ai)
; #pragma unroll
;             for (int m = 0; m < 4; ++m) {
;                 const int row = row0 + ai * HALF + m * 16;
;                 const float rs = rsv[ai * 4 + m];
;                 const f32x4 g0 = acc[ai][0][m][0], g1 = acc[ai][0][m][1], u0 = acc[ai][1][m][0], u1 = acc[ai][1][m][1];
;                 const f32x2 o0 = swiglu_pk((f32x2){g0[0], g0[1]}, (f32x2){u0[0], u0[1]}, rs), o1 = swiglu_pk((f32x2){g0[2], g0[3]}, (f32x2){u0[2], u0[3]}, rs);
;                 const f32x2 o2 = swiglu_pk((f32x2){g1[0], g1[1]}, (f32x2){u1[0], u1[1]}, rs), o3 = swiglu_pk((f32x2){g1[2], g1[3]}, (f32x2){u1[2], u1[3]}, rs);
;                 u32x4 w; w.x = pk2(o0.x, o0.y); w.y = pk2(o1.x, o1.y); w.z = pk2(o2.x, o2.y); w.w = pk2(o3.x, o3.y);
;                 __builtin_nontemporal_store(w, (u32x4*)(G + (size_t)(row >> 8) * ((size_t)BM * FF) + (size_t)(col0 >> 6) * (BM * BK) + (size_t)(row & 255) * BK + (col0 & 63)));
;                 __builtin_amdgcn_sched_barrier(0);
;             }
.LBB0_112:
	s_lshl_b32 s6, s46, 8
	s_add_i32 s41, s6, s35
	v_or_b32_e32 v154, s41, v129
	v_ashrrev_i32_e32 v155, 31, v154
	v_lshl_add_u64 v[150:151], v[154:155], 2, s[8:9]
	global_load_dword v132, v[150:151], off
	global_load_dword v141, v[150:151], off offset:64
	global_load_dword v142, v[150:151], off offset:128
	global_load_dword v144, v[150:151], off offset:192
	global_load_dword v146, v[150:151], off offset:512
	global_load_dword v148, v[150:151], off offset:576
	global_load_dword v152, v[150:151], off offset:640
	s_nop 0
	global_load_dword v150, v[150:151], off offset:704
	s_lshl_b32 s6, s61, 7
	s_or_b32 s6, s6, s39
	s_waitcnt vmcnt(0)
	v_fmamk_f32 v132, v132, 0x3a000000, v147
	v_fmamk_f32 v141, v141, 0x3a000000, v147
	v_fmamk_f32 v142, v142, 0x3a000000, v147
	v_fmamk_f32 v144, v144, 0x3a000000, v147
	v_fmamk_f32 v146, v146, 0x3a000000, v147
	v_fmamk_f32 v151, v148, 0x3a000000, v147
	v_fmamk_f32 v153, v152, 0x3a000000, v147
	v_fmamk_f32 v155, v150, 0x3a000000, v147
	v_rsq_f32_e32 v132, v132
	v_rsq_f32_e32 v156, v141
	v_rsq_f32_e32 v152, v142
	v_rsq_f32_e32 v150, v144
	v_rsq_f32_e32 v148, v146
	v_rsq_f32_e32 v146, v151
	v_rsq_f32_e32 v144, v153
	v_rsq_f32_e32 v142, v155
	v_add_u32_e32 v151, 0x80, v154
	v_mul_f32_e32 v124, v124, v132
	v_mul_f32_e32 v125, v125, v132
	v_mul_f32_e32 v126, v126, v132
	v_mul_f32_e32 v127, v127, v132
	v_mul_f32_e32 v158, s38, v124
	v_mul_f32_e32 v159, s38, v125
	v_mul_f32_e32 v160, s38, v126
	v_mul_f32_e32 v161, s38, v127
	v_exp_f32_e32 v158, v158
	v_exp_f32_e32 v159, v159
	v_exp_f32_e32 v160, v160
	v_exp_f32_e32 v161, v161
	v_mul_f32_e32 v116, v116, v132
	v_mul_f32_e32 v117, v117, v132
	v_add_f32_e32 v158, 1.0, v158
	v_add_f32_e32 v159, 1.0, v159
	v_mul_f32_e32 v118, v118, v132
	v_mul_f32_e32 v119, v119, v132
	v_rcp_f32_e32 v158, v158
	v_rcp_f32_e32 v159, v159
	v_add_f32_e32 v160, 1.0, v160
	v_add_f32_e32 v161, 1.0, v161
	v_mul_f32_e32 v120, v120, v132
	v_mul_f32_e32 v121, v121, v132
	v_rcp_f32_e32 v160, v160
	v_rcp_f32_e32 v161, v161
	v_mul_f32_e32 v124, v124, v158
	v_mul_f32_e32 v125, v125, v159
	v_mul_f32_e32 v122, v122, v132
	v_mul_f32_e32 v123, v123, v132
	v_mul_f32_e32 v116, v116, v124
	v_mul_f32_e32 v117, v117, v125
	v_mul_f32_e32 v124, v126, v160
	v_mul_f32_e32 v125, v127, v161
	v_mul_f32_e32 v126, s38, v122
	v_mul_f32_e32 v127, s38, v123
	v_mul_f32_e32 v118, v118, v124
	v_mul_f32_e32 v119, v119, v125
	v_mul_f32_e32 v124, s38, v120
	v_mul_f32_e32 v125, s38, v121
	v_exp_f32_e32 v126, v126
	v_exp_f32_e32 v124, v124
	v_exp_f32_e32 v125, v125
	v_exp_f32_e32 v127, v127
	s_ashr_i32 s6, s6, 6
	s_ashr_i32 s7, s6, 31
	v_add_f32_e32 v124, 1.0, v124
	v_add_f32_e32 v125, 1.0, v125
	v_add_f32_e32 v126, 1.0, v126
	v_add_f32_e32 v127, 1.0, v127
	v_rcp_f32_e32 v124, v124
	v_rcp_f32_e32 v125, v125
	v_rcp_f32_e32 v126, v126
	v_rcp_f32_e32 v127, v127
	s_ashr_i32 s41, s41, 8
	s_lshl_b64 s[6:7], s[6:7], 15
	s_mul_hi_i32 s46, s41, 0x2c0000
	s_mul_i32 s41, s41, 0x2c0000
	v_mul_f32_e32 v120, v120, v124
	v_mul_f32_e32 v121, v121, v125
	v_mul_f32_e32 v112, v112, v132
	v_mul_f32_e32 v113, v113, v132
	s_add_u32 s41, s30, s41
	v_mul_f32_e32 v120, v112, v120
	v_mul_f32_e32 v121, v113, v121
	v_mul_f32_e32 v112, v122, v126
	v_mul_f32_e32 v113, v123, v127
	v_mul_f32_e32 v114, v114, v132
	v_mul_f32_e32 v115, v115, v132
	s_addc_u32 s46, s31, s46
	v_mul_f32_e32 v122, v114, v112
	v_mul_f32_e32 v123, v115, v113
	v_cvt_pk_bf16_f32 v112, v116, v117
	s_add_u32 s48, s41, s6
	v_lshlrev_b32_e32 v116, 7, v154
	s_addc_u32 s49, s46, s7
	v_and_b32_e32 v132, 0x6780, v116
	v_lshl_add_u64 v[116:117], s[48:49], 0, v[132:133]
	v_mov_b32_e32 v141, v133
	v_lshl_add_u64 v[116:117], v[116:117], 0, v[140:141]
	v_cvt_pk_bf16_f32 v113, v118, v119
	v_cvt_pk_bf16_f32 v114, v120, v121
	v_cvt_pk_bf16_f32 v115, v122, v123
	global_store_dwordx4 v[116:117], v[112:115], off nt
	v_mul_f32_e32 v108, v108, v156
	v_mul_f32_e32 v109, v109, v156
	v_mul_f32_e32 v110, v110, v156
	v_mul_f32_e32 v111, v111, v156
	v_mul_f32_e32 v112, s38, v108
	v_mul_f32_e32 v113, s38, v109
	v_mul_f32_e32 v114, s38, v110
	v_mul_f32_e32 v115, s38, v111
	v_exp_f32_e32 v112, v112
	v_exp_f32_e32 v113, v113
	v_exp_f32_e32 v114, v114
	v_exp_f32_e32 v115, v115
	v_mul_f32_e32 v100, v100, v156
	v_mul_f32_e32 v101, v101, v156
	v_add_f32_e32 v112, 1.0, v112
	v_add_f32_e32 v113, 1.0, v113
	v_mul_f32_e32 v102, v102, v156
	v_mul_f32_e32 v103, v103, v156
	v_rcp_f32_e32 v112, v112
	v_rcp_f32_e32 v113, v113
	v_add_f32_e32 v114, 1.0, v114
	v_add_f32_e32 v115, 1.0, v115
	v_mul_f32_e32 v104, v104, v156
	v_mul_f32_e32 v105, v105, v156
	v_rcp_f32_e32 v114, v114
	v_rcp_f32_e32 v115, v115
	v_mul_f32_e32 v108, v108, v112
	v_mul_f32_e32 v109, v109, v113
	v_mul_f32_e32 v106, v106, v156
	v_mul_f32_e32 v107, v107, v156
	v_mul_f32_e32 v100, v100, v108
	v_mul_f32_e32 v101, v101, v109
	v_mul_f32_e32 v108, v110, v114
	v_mul_f32_e32 v109, v111, v115
	v_mul_f32_e32 v110, s38, v106
	v_mul_f32_e32 v111, s38, v107
	v_mul_f32_e32 v102, v102, v108
	v_mul_f32_e32 v103, v103, v109
	v_mul_f32_e32 v108, s38, v104
	v_mul_f32_e32 v109, s38, v105
	v_exp_f32_e32 v110, v110
	v_exp_f32_e32 v108, v108
	v_exp_f32_e32 v109, v109
	v_exp_f32_e32 v111, v111
	v_mul_f32_e32 v96, v96, v156
	v_mul_f32_e32 v97, v97, v156
	v_mul_f32_e32 v98, v98, v156
	v_mul_f32_e32 v99, v99, v156
	v_add_f32_e32 v108, 1.0, v108
	v_add_f32_e32 v109, 1.0, v109
	v_add_f32_e32 v110, 1.0, v110
	v_add_f32_e32 v111, 1.0, v111
	v_rcp_f32_e32 v108, v108
	v_rcp_f32_e32 v109, v109
	v_rcp_f32_e32 v110, v110
	v_rcp_f32_e32 v111, v111
	v_mul_f32_e32 v104, v104, v108
	v_mul_f32_e32 v105, v105, v109
	s_nop 0
	v_mul_f32_e32 v104, v96, v104
	v_mul_f32_e32 v105, v97, v105
; __device__ __forceinline__ unsigned pk2(float lo, float hi) { unsigned r; asm volatile("v_cvt_pk_bf16_f32 %0, %1, %2" : "=v"(r) : "v"(lo), "v"(hi)); return r; }
; __device__ __forceinline__ f32x2 swiglu_pk(f32x2 g, f32x2 u, float rs) {
;     const f32x2 t = g * rs, s = t * (-1.44269504089f);
;     f32x2 e; e.x = __builtin_amdgcn_exp2f(s.x); e.y = __builtin_amdgcn_exp2f(s.y);
;     const f32x2 d = e + 1.0f; f32x2 r; r.x = __builtin_amdgcn_rcpf(d.x); r.y = __builtin_amdgcn_rcpf(d.y);
;     return (t * r) * (u * rs);
; }
;     __device__ __forceinline__ void operator()(const f32x4 (&acc)[2][2][4][2], const Unit& u, int wr, int wc, int fr, int fq) const {
;     ...
;             for (int m = 0; m < 4; ++m) {
;                 const int row = row0 + ai * HALF + m * 16;
;                 const float rs = rsv[ai * 4 + m];
;                 const f32x4 g0 = acc[ai][0][m][0], g1 = acc[ai][0][m][1], u0 = acc[ai][1][m][0], u1 = acc[ai][1][m][1];
;                 const f32x2 o0 = swiglu_pk((f32x2){g0[0], g0[1]}, (f32x2){u0[0], u0[1]}, rs), o1 = swiglu_pk((f32x2){g0[2], g0[3]}, (f32x2){u0[2], u0[3]}, rs);
;                 const f32x2 o2 = swiglu_pk((f32x2){g1[0], g1[1]}, (f32x2){u1[0], u1[1]}, rs), o3 = swiglu_pk((f32x2){g1[2], g1[3]}, (f32x2){u1[2], u1[3]}, rs);
;                 u32x4 w; w.x = pk2(o0.x, o0.y); w.y = pk2(o1.x, o1.y); w.z = pk2(o2.x, o2.y); w.w = pk2(o3.x, o3.y);
;                 __builtin_nontemporal_store(w, (u32x4*)(G + (size_t)(row >> 8) * ((size_t)BM * FF) + (size_t)(col0 >> 6) * (BM * BK) + (size_t)(row & 255) * BK + (col0 & 63)));
;                 __builtin_amdgcn_sched_barrier(0);
	v_mul_f32_e32 v96, v106, v110
	v_mul_f32_e32 v97, v107, v111
	s_nop 0
	v_mul_f32_e32 v106, v98, v96
	v_mul_f32_e32 v107, v99, v97
	v_cvt_pk_bf16_f32 v96, v100, v101
	v_cvt_pk_bf16_f32 v97, v102, v103
	v_cvt_pk_bf16_f32 v98, v104, v105
	s_nop 0
	v_cvt_pk_bf16_f32 v99, v106, v107
	global_store_dwordx4 v[116:117], v[96:99], off offset:2048 nt
	v_mul_f32_e32 v92, v92, v152
	v_mul_f32_e32 v93, v93, v152
	v_mul_f32_e32 v94, v94, v152
	v_mul_f32_e32 v95, v95, v152
	v_mul_f32_e32 v96, s38, v92
	v_mul_f32_e32 v97, s38, v93
	v_mul_f32_e32 v98, s38, v94
	v_mul_f32_e32 v99, s38, v95
	v_exp_f32_e32 v96, v96
	v_exp_f32_e32 v97, v97
	v_exp_f32_e32 v98, v98
	v_exp_f32_e32 v99, v99
	v_mul_f32_e32 v84, v84, v152
	v_mul_f32_e32 v85, v85, v152
	v_add_f32_e32 v96, 1.0, v96
	v_add_f32_e32 v97, 1.0, v97
	v_mul_f32_e32 v86, v86, v152
	v_mul_f32_e32 v87, v87, v152
	v_rcp_f32_e32 v96, v96
	v_rcp_f32_e32 v97, v97
	v_add_f32_e32 v98, 1.0, v98
	v_add_f32_e32 v99, 1.0, v99
	v_mul_f32_e32 v88, v88, v152
	v_mul_f32_e32 v89, v89, v152
	v_rcp_f32_e32 v98, v98
	v_rcp_f32_e32 v99, v99
	v_mul_f32_e32 v92, v92, v96
	v_mul_f32_e32 v93, v93, v97
	v_mul_f32_e32 v90, v90, v152
	v_mul_f32_e32 v91, v91, v152
	v_mul_f32_e32 v84, v84, v92
	v_mul_f32_e32 v85, v85, v93
	v_mul_f32_e32 v92, v94, v98
	v_mul_f32_e32 v93, v95, v99
	v_mul_f32_e32 v94, s38, v90
	v_mul_f32_e32 v95, s38, v91
	v_mul_f32_e32 v86, v86, v92
	v_mul_f32_e32 v87, v87, v93
	v_mul_f32_e32 v92, s38, v88
	v_mul_f32_e32 v93, s38, v89
	v_exp_f32_e32 v94, v94
	v_exp_f32_e32 v92, v92
	v_exp_f32_e32 v93, v93
	v_exp_f32_e32 v95, v95
	v_mul_f32_e32 v80, v80, v152
	v_mul_f32_e32 v81, v81, v152
	v_mul_f32_e32 v82, v82, v152
	v_mul_f32_e32 v83, v83, v152
	v_add_f32_e32 v92, 1.0, v92
	v_add_f32_e32 v93, 1.0, v93
	v_add_f32_e32 v94, 1.0, v94
	v_add_f32_e32 v95, 1.0, v95
	v_rcp_f32_e32 v92, v92
	v_rcp_f32_e32 v93, v93
	v_rcp_f32_e32 v94, v94
	v_rcp_f32_e32 v95, v95
	v_mul_f32_e32 v88, v88, v92
	v_mul_f32_e32 v89, v89, v93
	s_nop 0
	v_mul_f32_e32 v88, v80, v88
	v_mul_f32_e32 v89, v81, v89
	v_mul_f32_e32 v80, v90, v94
	v_mul_f32_e32 v81, v91, v95
	s_nop 0
	v_mul_f32_e32 v90, v82, v80
	v_mul_f32_e32 v91, v83, v81
	v_cvt_pk_bf16_f32 v80, v84, v85
	v_add_co_u32_e32 v84, vcc, s59, v116
	v_cvt_pk_bf16_f32 v81, v86, v87
	v_cvt_pk_bf16_f32 v82, v88, v89
	v_cvt_pk_bf16_f32 v83, v90, v91
	s_nop 1
	v_addc_co_u32_e32 v85, vcc, 0, v117, vcc
	global_store_dwordx4 v[84:85], v[80:83], off nt
	v_mul_f32_e32 v76, v76, v150
	v_mul_f32_e32 v77, v77, v150
	v_mul_f32_e32 v78, v78, v150
	v_mul_f32_e32 v79, v79, v150
	v_mul_f32_e32 v80, s38, v76
	v_mul_f32_e32 v81, s38, v77
	v_mul_f32_e32 v82, s38, v78
	v_mul_f32_e32 v83, s38, v79
	v_exp_f32_e32 v80, v80
	v_exp_f32_e32 v81, v81
	v_exp_f32_e32 v82, v82
	v_exp_f32_e32 v83, v83
	v_mul_f32_e32 v68, v68, v150
	v_mul_f32_e32 v69, v69, v150
	v_add_f32_e32 v80, 1.0, v80
	v_add_f32_e32 v81, 1.0, v81
	v_mul_f32_e32 v70, v70, v150
	v_mul_f32_e32 v71, v71, v150
	v_rcp_f32_e32 v80, v80
	v_rcp_f32_e32 v81, v81
	v_add_f32_e32 v82, 1.0, v82
	v_add_f32_e32 v83, 1.0, v83
	v_mul_f32_e32 v72, v72, v150
	v_mul_f32_e32 v73, v73, v150
	v_rcp_f32_e32 v82, v82
	v_rcp_f32_e32 v83, v83
	v_mul_f32_e32 v76, v76, v80
	v_mul_f32_e32 v77, v77, v81
	v_mul_f32_e32 v74, v74, v150
	v_mul_f32_e32 v75, v75, v150
	v_mul_f32_e32 v68, v68, v76
	v_mul_f32_e32 v69, v69, v77
	v_mul_f32_e32 v76, v78, v82
	v_mul_f32_e32 v77, v79, v83
	v_mul_f32_e32 v78, s38, v74
	v_mul_f32_e32 v79, s38, v75
	v_mul_f32_e32 v70, v70, v76
	v_mul_f32_e32 v71, v71, v77
	v_mul_f32_e32 v76, s38, v72
	v_mul_f32_e32 v77, s38, v73
	v_exp_f32_e32 v78, v78
	v_exp_f32_e32 v76, v76
	v_exp_f32_e32 v77, v77
	v_exp_f32_e32 v79, v79
	v_mul_f32_e32 v64, v64, v150
	v_mul_f32_e32 v65, v65, v150
	v_mul_f32_e32 v66, v66, v150
	v_mul_f32_e32 v67, v67, v150
	v_add_f32_e32 v76, 1.0, v76
	v_add_f32_e32 v77, 1.0, v77
	v_add_f32_e32 v78, 1.0, v78
	v_add_f32_e32 v79, 1.0, v79
	v_rcp_f32_e32 v76, v76
	v_rcp_f32_e32 v77, v77
	v_rcp_f32_e32 v78, v78
	v_rcp_f32_e32 v79, v79
	v_mul_f32_e32 v72, v72, v76
	v_mul_f32_e32 v73, v73, v77
	s_nop 0
	v_mul_f32_e32 v72, v64, v72
	v_mul_f32_e32 v73, v65, v73
	v_mul_f32_e32 v64, v74, v78
	v_mul_f32_e32 v65, v75, v79
	s_nop 0
	v_mul_f32_e32 v74, v66, v64
	v_mul_f32_e32 v75, v67, v65
	v_cvt_pk_bf16_f32 v64, v68, v69
	v_cvt_pk_bf16_f32 v65, v70, v71
	v_cvt_pk_bf16_f32 v66, v72, v73
	s_nop 0
	v_cvt_pk_bf16_f32 v67, v74, v75
	global_store_dwordx4 v[84:85], v[64:67], off offset:2048 nt
	v_mul_f32_e32 v60, v60, v148
	v_mul_f32_e32 v61, v61, v148
	v_mul_f32_e32 v62, v62, v148
	v_mul_f32_e32 v63, v63, v148
	v_mul_f32_e32 v66, s38, v60
	v_mul_f32_e32 v67, s38, v61
	v_mul_f32_e32 v68, s38, v62
	v_mul_f32_e32 v69, s38, v63
	v_exp_f32_e32 v66, v66
	v_exp_f32_e32 v67, v67
	v_exp_f32_e32 v68, v68
	v_exp_f32_e32 v69, v69
	v_mul_f32_e32 v52, v52, v148
	v_mul_f32_e32 v53, v53, v148
	v_add_f32_e32 v66, 1.0, v66
	v_add_f32_e32 v67, 1.0, v67
	v_mul_f32_e32 v54, v54, v148
	v_mul_f32_e32 v55, v55, v148
	v_rcp_f32_e32 v66, v66
	v_rcp_f32_e32 v67, v67
	v_add_f32_e32 v68, 1.0, v68
	v_add_f32_e32 v69, 1.0, v69
	v_mul_f32_e32 v56, v56, v148
	v_mul_f32_e32 v57, v57, v148
	v_rcp_f32_e32 v68, v68
	v_rcp_f32_e32 v69, v69
	v_mul_f32_e32 v60, v60, v66
	v_mul_f32_e32 v61, v61, v67
	v_mul_f32_e32 v58, v58, v148
	v_mul_f32_e32 v59, v59, v148
	v_mul_f32_e32 v52, v52, v60
	v_mul_f32_e32 v53, v53, v61
	v_mul_f32_e32 v60, v62, v68
	v_mul_f32_e32 v61, v63, v69
	v_mul_f32_e32 v62, s38, v58
	v_mul_f32_e32 v63, s38, v59
	v_mul_f32_e32 v54, v54, v60
	v_mul_f32_e32 v55, v55, v61
	v_mul_f32_e32 v60, s38, v56
	v_mul_f32_e32 v61, s38, v57
	v_exp_f32_e32 v62, v62
	v_exp_f32_e32 v60, v60
	v_exp_f32_e32 v61, v61
; __device__ __forceinline__ unsigned pk2(float lo, float hi) { unsigned r; asm volatile("v_cvt_pk_bf16_f32 %0, %1, %2" : "=v"(r) : "v"(lo), "v"(hi)); return r; }
; __device__ __forceinline__ f32x2 swiglu_pk(f32x2 g, f32x2 u, float rs) {
;     const f32x2 t = g * rs, s = t * (-1.44269504089f);
;     f32x2 e; e.x = __builtin_amdgcn_exp2f(s.x); e.y = __builtin_amdgcn_exp2f(s.y);
;     const f32x2 d = e + 1.0f; f32x2 r; r.x = __builtin_amdgcn_rcpf(d.x); r.y = __builtin_amdgcn_rcpf(d.y);
;     return (t * r) * (u * rs);
; }
;     __device__ __forceinline__ void operator()(const f32x4 (&acc)[2][2][4][2], const Unit& u, int wr, int wc, int fr, int fq) const {
;     ...
;             for (int m = 0; m < 4; ++m) {
;                 const int row = row0 + ai * HALF + m * 16;
;                 const float rs = rsv[ai * 4 + m];
;                 const f32x4 g0 = acc[ai][0][m][0], g1 = acc[ai][0][m][1], u0 = acc[ai][1][m][0], u1 = acc[ai][1][m][1];
;                 const f32x2 o0 = swiglu_pk((f32x2){g0[0], g0[1]}, (f32x2){u0[0], u0[1]}, rs), o1 = swiglu_pk((f32x2){g0[2], g0[3]}, (f32x2){u0[2], u0[3]}, rs);
;                 const f32x2 o2 = swiglu_pk((f32x2){g1[0], g1[1]}, (f32x2){u1[0], u1[1]}, rs), o3 = swiglu_pk((f32x2){g1[2], g1[3]}, (f32x2){u1[2], u1[3]}, rs);
;                 u32x4 w; w.x = pk2(o0.x, o0.y); w.y = pk2(o1.x, o1.y); w.z = pk2(o2.x, o2.y); w.w = pk2(o3.x, o3.y);
;                 __builtin_nontemporal_store(w, (u32x4*)(G + (size_t)(row >> 8) * ((size_t)BM * FF) + (size_t)(col0 >> 6) * (BM * BK) + (size_t)(row & 255) * BK + (col0 & 63)));
;                 __builtin_amdgcn_sched_barrier(0);
	v_exp_f32_e32 v63, v63
	v_lshrrev_b32_e32 v64, 8, v151
	v_mul_f32_e32 v48, v48, v148
	v_mul_f32_e32 v49, v49, v148
	v_add_f32_e32 v60, 1.0, v60
	v_add_f32_e32 v61, 1.0, v61
	v_add_f32_e32 v62, 1.0, v62
	v_add_f32_e32 v63, 1.0, v63
	v_rcp_f32_e32 v60, v60
	v_rcp_f32_e32 v61, v61
	v_rcp_f32_e32 v62, v62
	v_rcp_f32_e32 v63, v63
	v_mul_hi_i32_i24_e32 v65, 0x2c0000, v64
	v_mul_f32_e32 v56, v56, v60
	v_mul_f32_e32 v57, v57, v61
	v_mul_i32_i24_e32 v64, 0x2c0000, v64
	v_mul_f32_e32 v56, v48, v56
	v_mul_f32_e32 v57, v49, v57
	v_mul_f32_e32 v48, v58, v62
	v_mul_f32_e32 v49, v59, v63
	v_mul_f32_e32 v50, v50, v148
	v_mul_f32_e32 v51, v51, v148
	s_nop 0
	v_mul_f32_e32 v58, v50, v48
	v_mul_f32_e32 v59, v51, v49
	v_cvt_pk_bf16_f32 v48, v52, v53
	v_cvt_pk_bf16_f32 v49, v54, v55
	v_lshl_add_u64 v[52:53], s[30:31], 0, v[64:65]
	v_lshlrev_b32_e32 v54, 7, v151
	v_lshl_add_u64 v[52:53], v[52:53], 0, s[6:7]
	v_and_b32_e32 v132, 0x6780, v54
	v_lshl_add_u64 v[52:53], v[52:53], 0, v[132:133]
	v_lshl_add_u64 v[52:53], v[52:53], 0, v[140:141]
	v_cvt_pk_bf16_f32 v50, v56, v57
	v_cvt_pk_bf16_f32 v51, v58, v59
	global_store_dwordx4 v[52:53], v[48:51], off nt
	v_mul_f32_e32 v44, v44, v146
	v_mul_f32_e32 v45, v45, v146
	v_mul_f32_e32 v46, v46, v146
	v_mul_f32_e32 v47, v47, v146
	v_mul_f32_e32 v48, s38, v44
	v_mul_f32_e32 v49, s38, v45
	v_mul_f32_e32 v50, s38, v46
	v_mul_f32_e32 v51, s38, v47
	v_exp_f32_e32 v48, v48
	v_exp_f32_e32 v49, v49
	v_exp_f32_e32 v50, v50
	v_exp_f32_e32 v51, v51
	v_mul_f32_e32 v36, v36, v146
	v_mul_f32_e32 v37, v37, v146
	v_add_f32_e32 v48, 1.0, v48
	v_add_f32_e32 v49, 1.0, v49
	v_mul_f32_e32 v38, v38, v146
	v_mul_f32_e32 v39, v39, v146
	v_rcp_f32_e32 v48, v48
	v_rcp_f32_e32 v49, v49
	v_add_f32_e32 v50, 1.0, v50
	v_add_f32_e32 v51, 1.0, v51
	v_mul_f32_e32 v40, v40, v146
	v_mul_f32_e32 v41, v41, v146
	v_rcp_f32_e32 v50, v50
	v_rcp_f32_e32 v51, v51
	v_mul_f32_e32 v44, v44, v48
	v_mul_f32_e32 v45, v45, v49
	v_mul_f32_e32 v42, v42, v146
	v_mul_f32_e32 v43, v43, v146
	v_mul_f32_e32 v36, v36, v44
	v_mul_f32_e32 v37, v37, v45
	v_mul_f32_e32 v44, v46, v50
	v_mul_f32_e32 v45, v47, v51
	v_mul_f32_e32 v46, s38, v42
	v_mul_f32_e32 v47, s38, v43
	v_mul_f32_e32 v38, v38, v44
	v_mul_f32_e32 v39, v39, v45
	v_mul_f32_e32 v44, s38, v40
	v_mul_f32_e32 v45, s38, v41
	v_exp_f32_e32 v46, v46
	v_exp_f32_e32 v44, v44
	v_exp_f32_e32 v45, v45
	v_exp_f32_e32 v47, v47
	v_mul_f32_e32 v32, v32, v146
	v_mul_f32_e32 v33, v33, v146
	v_mul_f32_e32 v34, v34, v146
	v_mul_f32_e32 v35, v35, v146
	v_add_f32_e32 v44, 1.0, v44
	v_add_f32_e32 v45, 1.0, v45
	v_add_f32_e32 v46, 1.0, v46
	v_add_f32_e32 v47, 1.0, v47
	v_rcp_f32_e32 v44, v44
	v_rcp_f32_e32 v45, v45
	v_rcp_f32_e32 v46, v46
	v_rcp_f32_e32 v47, v47
	v_mul_f32_e32 v40, v40, v44
	v_mul_f32_e32 v41, v41, v45
	s_nop 0
	v_mul_f32_e32 v40, v32, v40
	v_mul_f32_e32 v41, v33, v41
	v_mul_f32_e32 v32, v42, v46
	v_mul_f32_e32 v33, v43, v47
	s_nop 0
	v_mul_f32_e32 v42, v34, v32
	v_mul_f32_e32 v43, v35, v33
	v_cvt_pk_bf16_f32 v32, v36, v37
	v_cvt_pk_bf16_f32 v33, v38, v39
	v_cvt_pk_bf16_f32 v34, v40, v41
	s_nop 0
	v_cvt_pk_bf16_f32 v35, v42, v43
	global_store_dwordx4 v[52:53], v[32:35], off offset:2048 nt
	v_mul_f32_e32 v28, v28, v144
	v_mul_f32_e32 v29, v29, v144
	v_mul_f32_e32 v30, v30, v144
	v_mul_f32_e32 v31, v31, v144
	v_mul_f32_e32 v32, s38, v28
	v_mul_f32_e32 v33, s38, v29
	v_mul_f32_e32 v34, s38, v30
	v_mul_f32_e32 v35, s38, v31
	v_exp_f32_e32 v32, v32
	v_exp_f32_e32 v33, v33
	v_exp_f32_e32 v34, v34
	v_exp_f32_e32 v35, v35
	v_mul_f32_e32 v20, v20, v144
	v_mul_f32_e32 v21, v21, v144
	v_add_f32_e32 v32, 1.0, v32
	v_add_f32_e32 v33, 1.0, v33
	v_mul_f32_e32 v22, v22, v144
	v_mul_f32_e32 v23, v23, v144
; __device__ __forceinline__ unsigned pk2(float lo, float hi) { unsigned r; asm volatile("v_cvt_pk_bf16_f32 %0, %1, %2" : "=v"(r) : "v"(lo), "v"(hi)); return r; }
; #define PG8_BAR __builtin_amdgcn_s_barrier()
; template <class Epi>
; __device__ __forceinline__ void gemm_phase(LAS unsigned char* lds, const Gemm g, const StaticOrder& S, const Epi& E) {
;     ...
;         if (wr == 0) PG8_BAR;
;         E(acc, cur, wr, wc, fr, fq);
;         if (!has_next) break;
; #pragma unroll
;         for (int a = 0; a < 2; ++a)
; #pragma unroll
;             for (int b = 0; b < 2; ++b)
; #pragma unroll
;                 for (int m = 0; m < 4; ++m)
; #pragma unroll
;                     for (int n = 0; n < 2; ++n) acc[a][b][m][n] = (f32x4){0.f, 0.f, 0.f, 0.f};
;         cur = nxt; cA = nA; cB = nB; ++ui;
;         if (wr == 1) PG8_BAR;
;     }
;     __device__ __forceinline__ void operator()(const f32x4 (&acc)[2][2][4][2], const Unit& u, int wr, int wc, int fr, int fq) const {
;     ...
;             for (int m = 0; m < 4; ++m) {
;                 const int row = row0 + ai * HALF + m * 16;
;                 const float rs = rsv[ai * 4 + m];
;                 const f32x4 g0 = acc[ai][0][m][0], g1 = acc[ai][0][m][1], u0 = acc[ai][1][m][0], u1 = acc[ai][1][m][1];
;                 const f32x2 o0 = swiglu_pk((f32x2){g0[0], g0[1]}, (f32x2){u0[0], u0[1]}, rs), o1 = swiglu_pk((f32x2){g0[2], g0[3]}, (f32x2){u0[2], u0[3]}, rs);
;                 const f32x2 o2 = swiglu_pk((f32x2){g1[0], g1[1]}, (f32x2){u1[0], u1[1]}, rs), o3 = swiglu_pk((f32x2){g1[2], g1[3]}, (f32x2){u1[2], u1[3]}, rs);
;                 u32x4 w; w.x = pk2(o0.x, o0.y); w.y = pk2(o1.x, o1.y); w.z = pk2(o2.x, o2.y); w.w = pk2(o3.x, o3.y);
;                 __builtin_nontemporal_store(w, (u32x4*)(G + (size_t)(row >> 8) * ((size_t)BM * FF) + (size_t)(col0 >> 6) * (BM * BK) + (size_t)(row & 255) * BK + (col0 & 63)));
;                 __builtin_amdgcn_sched_barrier(0);
;             }
	v_rcp_f32_e32 v32, v32
	v_rcp_f32_e32 v33, v33
	v_add_f32_e32 v34, 1.0, v34
	v_add_f32_e32 v35, 1.0, v35
	v_mul_f32_e32 v24, v24, v144
	v_mul_f32_e32 v25, v25, v144
	v_rcp_f32_e32 v34, v34
	v_rcp_f32_e32 v35, v35
	v_mul_f32_e32 v28, v28, v32
	v_mul_f32_e32 v29, v29, v33
	v_mul_f32_e32 v26, v26, v144
	v_mul_f32_e32 v27, v27, v144
	v_mul_f32_e32 v20, v20, v28
	v_mul_f32_e32 v21, v21, v29
	v_mul_f32_e32 v28, v30, v34
	v_mul_f32_e32 v29, v31, v35
	v_mul_f32_e32 v30, s38, v26
	v_mul_f32_e32 v31, s38, v27
	v_mul_f32_e32 v22, v22, v28
	v_mul_f32_e32 v23, v23, v29
	v_mul_f32_e32 v28, s38, v24
	v_mul_f32_e32 v29, s38, v25
	v_exp_f32_e32 v30, v30
	v_exp_f32_e32 v28, v28
	v_exp_f32_e32 v29, v29
	v_exp_f32_e32 v31, v31
	v_mul_f32_e32 v16, v16, v144
	v_mul_f32_e32 v17, v17, v144
	v_mul_f32_e32 v18, v18, v144
	v_mul_f32_e32 v19, v19, v144
	v_add_f32_e32 v28, 1.0, v28
	v_add_f32_e32 v29, 1.0, v29
	v_add_f32_e32 v30, 1.0, v30
	v_add_f32_e32 v31, 1.0, v31
	v_rcp_f32_e32 v28, v28
	v_rcp_f32_e32 v29, v29
	v_rcp_f32_e32 v30, v30
	v_rcp_f32_e32 v31, v31
	v_mul_f32_e32 v24, v24, v28
	v_mul_f32_e32 v25, v25, v29
	s_nop 0
	v_mul_f32_e32 v24, v16, v24
	v_mul_f32_e32 v25, v17, v25
	v_mul_f32_e32 v16, v26, v30
	v_mul_f32_e32 v17, v27, v31
	s_nop 0
	v_mul_f32_e32 v26, v18, v16
	v_mul_f32_e32 v27, v19, v17
	v_cvt_pk_bf16_f32 v16, v20, v21
	v_add_co_u32_e32 v20, vcc, s59, v52
	v_cvt_pk_bf16_f32 v17, v22, v23
	v_cvt_pk_bf16_f32 v18, v24, v25
	v_cvt_pk_bf16_f32 v19, v26, v27
	s_nop 1
	v_addc_co_u32_e32 v21, vcc, 0, v53, vcc
	global_store_dwordx4 v[20:21], v[16:19], off nt
	v_mul_f32_e32 v12, v12, v142
	v_mul_f32_e32 v13, v13, v142
	v_mul_f32_e32 v14, v14, v142
	v_mul_f32_e32 v15, v15, v142
	v_mul_f32_e32 v16, s38, v12
	v_mul_f32_e32 v17, s38, v13
	v_mul_f32_e32 v18, s38, v14
	v_mul_f32_e32 v19, s38, v15
	v_exp_f32_e32 v16, v16
	v_exp_f32_e32 v17, v17
	v_exp_f32_e32 v18, v18
	v_exp_f32_e32 v19, v19
	v_mul_f32_e32 v4, v4, v142
	v_mul_f32_e32 v5, v5, v142
	v_add_f32_e32 v16, 1.0, v16
	v_add_f32_e32 v17, 1.0, v17
	v_mul_f32_e32 v6, v6, v142
	v_mul_f32_e32 v7, v7, v142
	v_rcp_f32_e32 v16, v16
	v_rcp_f32_e32 v17, v17
	v_add_f32_e32 v18, 1.0, v18
	v_add_f32_e32 v19, 1.0, v19
	v_mul_f32_e32 v8, v8, v142
	v_mul_f32_e32 v9, v9, v142
	v_rcp_f32_e32 v18, v18
	v_rcp_f32_e32 v19, v19
	v_mul_f32_e32 v12, v12, v16
	v_mul_f32_e32 v13, v13, v17
	v_mul_f32_e32 v10, v10, v142
	v_mul_f32_e32 v11, v11, v142
	v_mul_f32_e32 v4, v4, v12
	v_mul_f32_e32 v5, v5, v13
	v_mul_f32_e32 v12, v14, v18
	v_mul_f32_e32 v13, v15, v19
	v_mul_f32_e32 v14, s38, v10
	v_mul_f32_e32 v15, s38, v11
	v_mul_f32_e32 v6, v6, v12
	v_mul_f32_e32 v7, v7, v13
	v_mul_f32_e32 v12, s38, v8
	v_mul_f32_e32 v13, s38, v9
	v_exp_f32_e32 v14, v14
	v_exp_f32_e32 v12, v12
	v_exp_f32_e32 v13, v13
	v_exp_f32_e32 v15, v15
	v_mul_f32_e32 v0, v0, v142
	v_mul_f32_e32 v1, v1, v142
	v_mul_f32_e32 v2, v2, v142
	v_mul_f32_e32 v3, v3, v142
	v_add_f32_e32 v12, 1.0, v12
	v_add_f32_e32 v13, 1.0, v13
	v_add_f32_e32 v14, 1.0, v14
	v_add_f32_e32 v15, 1.0, v15
	v_rcp_f32_e32 v12, v12
	v_rcp_f32_e32 v13, v13
	v_rcp_f32_e32 v14, v14
	v_rcp_f32_e32 v15, v15
	v_mul_f32_e32 v8, v8, v12
	v_mul_f32_e32 v9, v9, v13
	s_nop 0
	v_mul_f32_e32 v8, v0, v8
	v_mul_f32_e32 v9, v1, v9
	v_mul_f32_e32 v0, v10, v14
	v_mul_f32_e32 v1, v11, v15
	s_nop 0
	v_mul_f32_e32 v10, v2, v0
	v_mul_f32_e32 v11, v3, v1
	v_cvt_pk_bf16_f32 v0, v4, v5
	v_cvt_pk_bf16_f32 v1, v6, v7
	v_cvt_pk_bf16_f32 v2, v8, v9
	s_nop 0
	v_cvt_pk_bf16_f32 v3, v10, v11
	global_store_dwordx4 v[20:21], v[0:3], off offset:2048 nt
	s_and_b64 vcc, exec, s[4:5]
	s_mov_b64 s[4:5], -1
	s_cbranch_vccnz .LBB0_103
	s_andn2_b64 vcc, exec, s[22:23]
	s_cbranch_vccnz .LBB0_102
	s_barrier
	s_branch .LBB0_102

; __device__ __forceinline__ unsigned pk2(float lo, float hi) { unsigned r; asm volatile("v_cvt_pk_bf16_f32 %0, %1, %2" : "=v"(r) : "v"(lo), "v"(hi)); return r; }
; __device__ __forceinline__ f32x2 swiglu_pk(f32x2 g, f32x2 u, float rs) {
;     const f32x2 t = g * rs, s = t * (-1.44269504089f);
;     f32x2 e; e.x = __builtin_amdgcn_exp2f(s.x); e.y = __builtin_amdgcn_exp2f(s.y);
;     const f32x2 d = e + 1.0f; f32x2 r; r.x = __builtin_amdgcn_rcpf(d.x); r.y = __builtin_amdgcn_rcpf(d.y);
;     return (t * r) * (u * rs);
; }
;     __device__ __forceinline__ void operator()(const f32x4 (&acc)[2][2][4][2], const Unit& u, int wr, int wc, int fr, int fq) const {
;         const int row0 = u.pm * BM + wr * 64 + fr, col0 = u.pn * 128 + wc * 32 + 8 * fq;
;         float rsv[8];
; #pragma unroll
;         for (int i = 0; i < 8; ++i) rsv[i] = ss[row0 + (i >> 2) * HALF + (i & 3) * 16];
; #pragma unroll
;         for (int i = 0; i < 8; ++i) rsv[i] = __builtin_amdgcn_rsqf(rsv[i] * (1.0f / D) + EPS);
;         __builtin_amdgcn_sched_barrier(0);
; #pragma unroll
;         for (int ai = 0; ai < 2; ++ai)
; #pragma unroll
;             for (int m = 0; m < 4; ++m) {
;                 const int row = row0 + ai * HALF + m * 16;
;                 const float rs = rsv[ai * 4 + m];
;                 const f32x4 g0 = acc[ai][0][m][0], g1 = acc[ai][0][m][1], u0 = acc[ai][1][m][0], u1 = acc[ai][1][m][1];
;                 const f32x2 o0 = swiglu_pk((f32x2){g0[0], g0[1]}, (f32x2){u0[0], u0[1]}, rs), o1 = swiglu_pk((f32x2){g0[2], g0[3]}, (f32x2){u0[2], u0[3]}, rs);
;                 const f32x2 o2 = swiglu_pk((f32x2){g1[0], g1[1]}, (f32x2){u1[0], u1[1]}, rs), o3 = swiglu_pk((f32x2){g1[2], g1[3]}, (f32x2){u1[2], u1[3]}, rs);
;                 u32x4 w; w.x = pk2(o0.x, o0.y); w.y = pk2(o1.x, o1.y); w.z = pk2(o2.x, o2.y); w.w = pk2(o3.x, o3.y);
;                 __builtin_nontemporal_store(w, (u32x4*)(G + (size_t)(row >> 8) * ((size_t)BM * FF) + (size_t)(col0 >> 6) * (BM * BK) + (size_t)(row & 255) * BK + (col0 & 63)));
;                 __builtin_amdgcn_sched_barrier(0);
;             }
.LBB0_1210:
	s_lshl_b32 s10, s50, 8
	s_add_i32 s45, s10, s26
	v_or_b32_e32 v154, s45, v129
	v_ashrrev_i32_e32 v155, 31, v154
	v_lshl_add_u64 v[150:151], v[154:155], 2, s[38:39]
	global_load_dword v132, v[150:151], off
	global_load_dword v141, v[150:151], off offset:64
	global_load_dword v142, v[150:151], off offset:128
	global_load_dword v144, v[150:151], off offset:192
	global_load_dword v146, v[150:151], off offset:512
	global_load_dword v148, v[150:151], off offset:576
	global_load_dword v152, v[150:151], off offset:640
	s_nop 0
	global_load_dword v150, v[150:151], off offset:704
	s_lshl_b32 s10, s63, 7
	s_or_b32 s10, s10, s27
	s_waitcnt vmcnt(0)
	v_fmamk_f32 v132, v132, 0x3a000000, v147
	v_fmamk_f32 v141, v141, 0x3a000000, v147
	v_fmamk_f32 v142, v142, 0x3a000000, v147
	v_fmamk_f32 v144, v144, 0x3a000000, v147
	v_fmamk_f32 v146, v146, 0x3a000000, v147
	v_fmamk_f32 v151, v148, 0x3a000000, v147
	v_fmamk_f32 v153, v152, 0x3a000000, v147
	v_fmamk_f32 v155, v150, 0x3a000000, v147
	v_rsq_f32_e32 v132, v132
	v_rsq_f32_e32 v156, v141
	v_rsq_f32_e32 v152, v142
	v_rsq_f32_e32 v150, v144
	v_rsq_f32_e32 v148, v146
	v_rsq_f32_e32 v146, v151
	v_rsq_f32_e32 v144, v153
	v_rsq_f32_e32 v142, v155
	v_add_u32_e32 v151, 0x80, v154
	v_mul_f32_e32 v124, v124, v132
	v_mul_f32_e32 v125, v125, v132
	v_mul_f32_e32 v126, v126, v132
	v_mul_f32_e32 v127, v127, v132
	v_mul_f32_e32 v158, s42, v124
	v_mul_f32_e32 v159, s42, v125
	v_mul_f32_e32 v160, s42, v126
	v_mul_f32_e32 v161, s42, v127
	v_exp_f32_e32 v158, v158
	v_exp_f32_e32 v159, v159
	v_exp_f32_e32 v160, v160
	v_exp_f32_e32 v161, v161
	v_mul_f32_e32 v116, v116, v132
	v_mul_f32_e32 v117, v117, v132
	v_add_f32_e32 v158, 1.0, v158
	v_add_f32_e32 v159, 1.0, v159
	v_mul_f32_e32 v118, v118, v132
	v_mul_f32_e32 v119, v119, v132
	v_rcp_f32_e32 v158, v158
	v_rcp_f32_e32 v159, v159
	v_add_f32_e32 v160, 1.0, v160
	v_add_f32_e32 v161, 1.0, v161
	v_mul_f32_e32 v120, v120, v132
	v_mul_f32_e32 v121, v121, v132
	v_rcp_f32_e32 v160, v160
	v_rcp_f32_e32 v161, v161
	v_mul_f32_e32 v124, v124, v158
	v_mul_f32_e32 v125, v125, v159
	v_mul_f32_e32 v122, v122, v132
	v_mul_f32_e32 v123, v123, v132
	v_mul_f32_e32 v116, v116, v124
	v_mul_f32_e32 v117, v117, v125
	v_mul_f32_e32 v124, v126, v160
	v_mul_f32_e32 v125, v127, v161
	v_mul_f32_e32 v126, s42, v122
	v_mul_f32_e32 v127, s42, v123
	v_mul_f32_e32 v118, v118, v124
	v_mul_f32_e32 v119, v119, v125
	v_mul_f32_e32 v124, s42, v120
	v_mul_f32_e32 v125, s42, v121
	v_exp_f32_e32 v126, v126
	v_exp_f32_e32 v124, v124
	v_exp_f32_e32 v125, v125
	v_exp_f32_e32 v127, v127
	s_ashr_i32 s10, s10, 6
	s_ashr_i32 s11, s10, 31
	v_add_f32_e32 v124, 1.0, v124
	v_add_f32_e32 v125, 1.0, v125
	v_add_f32_e32 v126, 1.0, v126
	v_add_f32_e32 v127, 1.0, v127
	v_rcp_f32_e32 v124, v124
	v_rcp_f32_e32 v125, v125
	v_rcp_f32_e32 v126, v126
	v_rcp_f32_e32 v127, v127
	s_ashr_i32 s45, s45, 8
	s_lshl_b64 s[10:11], s[10:11], 15
	s_mul_hi_i32 s50, s45, 0x2c0000
	s_mul_i32 s45, s45, 0x2c0000
	v_mul_f32_e32 v120, v120, v124
	v_mul_f32_e32 v121, v121, v125
	v_mul_f32_e32 v112, v112, v132
	v_mul_f32_e32 v113, v113, v132
	s_add_u32 s45, s36, s45
	v_mul_f32_e32 v120, v112, v120
	v_mul_f32_e32 v121, v113, v121
	v_mul_f32_e32 v112, v122, v126
	v_mul_f32_e32 v113, v123, v127
	v_mul_f32_e32 v114, v114, v132
	v_mul_f32_e32 v115, v115, v132
	s_addc_u32 s50, s37, s50
	v_mul_f32_e32 v122, v114, v112
	v_mul_f32_e32 v123, v115, v113
	v_cvt_pk_bf16_f32 v112, v116, v117
	s_add_u32 s52, s45, s10
	v_lshlrev_b32_e32 v116, 7, v154
	s_addc_u32 s53, s50, s11
	v_and_b32_e32 v132, 0x6780, v116
	v_lshl_add_u64 v[116:117], s[52:53], 0, v[132:133]
	v_mov_b32_e32 v141, v133
	v_lshl_add_u64 v[116:117], v[116:117], 0, v[140:141]
	v_cvt_pk_bf16_f32 v113, v118, v119
	v_cvt_pk_bf16_f32 v114, v120, v121
	v_cvt_pk_bf16_f32 v115, v122, v123
	global_store_dwordx4 v[116:117], v[112:115], off nt
	v_mul_f32_e32 v108, v108, v156
	v_mul_f32_e32 v109, v109, v156
	v_mul_f32_e32 v110, v110, v156
	v_mul_f32_e32 v111, v111, v156
	v_mul_f32_e32 v112, s42, v108
	v_mul_f32_e32 v113, s42, v109
	v_mul_f32_e32 v114, s42, v110
	v_mul_f32_e32 v115, s42, v111
	v_exp_f32_e32 v112, v112
	v_exp_f32_e32 v113, v113
	v_exp_f32_e32 v114, v114
	v_exp_f32_e32 v115, v115
	v_mul_f32_e32 v100, v100, v156
	v_mul_f32_e32 v101, v101, v156
	v_add_f32_e32 v112, 1.0, v112
	v_add_f32_e32 v113, 1.0, v113
	v_mul_f32_e32 v102, v102, v156
	v_mul_f32_e32 v103, v103, v156
	v_rcp_f32_e32 v112, v112
	v_rcp_f32_e32 v113, v113
	v_add_f32_e32 v114, 1.0, v114
	v_add_f32_e32 v115, 1.0, v115
	v_mul_f32_e32 v104, v104, v156
	v_mul_f32_e32 v105, v105, v156
	v_rcp_f32_e32 v114, v114
	v_rcp_f32_e32 v115, v115
	v_mul_f32_e32 v108, v108, v112
	v_mul_f32_e32 v109, v109, v113
	v_mul_f32_e32 v106, v106, v156
	v_mul_f32_e32 v107, v107, v156
	v_mul_f32_e32 v100, v100, v108
	v_mul_f32_e32 v101, v101, v109
	v_mul_f32_e32 v108, v110, v114
	v_mul_f32_e32 v109, v111, v115
	v_mul_f32_e32 v110, s42, v106
	v_mul_f32_e32 v111, s42, v107
	v_mul_f32_e32 v102, v102, v108
	v_mul_f32_e32 v103, v103, v109
	v_mul_f32_e32 v108, s42, v104
	v_mul_f32_e32 v109, s42, v105
	v_exp_f32_e32 v110, v110
	v_exp_f32_e32 v108, v108
	v_exp_f32_e32 v109, v109
	v_exp_f32_e32 v111, v111
	v_mul_f32_e32 v96, v96, v156
	v_mul_f32_e32 v97, v97, v156
	v_mul_f32_e32 v98, v98, v156
	v_mul_f32_e32 v99, v99, v156
	v_add_f32_e32 v108, 1.0, v108
	v_add_f32_e32 v109, 1.0, v109
	v_add_f32_e32 v110, 1.0, v110
	v_add_f32_e32 v111, 1.0, v111
	v_rcp_f32_e32 v108, v108
	v_rcp_f32_e32 v109, v109
	v_rcp_f32_e32 v110, v110
	v_rcp_f32_e32 v111, v111
	v_mul_f32_e32 v104, v104, v108
	v_mul_f32_e32 v105, v105, v109
	s_nop 0
	v_mul_f32_e32 v104, v96, v104
	v_mul_f32_e32 v105, v97, v105
; __device__ __forceinline__ unsigned pk2(float lo, float hi) { unsigned r; asm volatile("v_cvt_pk_bf16_f32 %0, %1, %2" : "=v"(r) : "v"(lo), "v"(hi)); return r; }
; __device__ __forceinline__ f32x2 swiglu_pk(f32x2 g, f32x2 u, float rs) {
;     const f32x2 t = g * rs, s = t * (-1.44269504089f);
;     f32x2 e; e.x = __builtin_amdgcn_exp2f(s.x); e.y = __builtin_amdgcn_exp2f(s.y);
;     const f32x2 d = e + 1.0f; f32x2 r; r.x = __builtin_amdgcn_rcpf(d.x); r.y = __builtin_amdgcn_rcpf(d.y);
;     return (t * r) * (u * rs);
; }
;     __device__ __forceinline__ void operator()(const f32x4 (&acc)[2][2][4][2], const Unit& u, int wr, int wc, int fr, int fq) const {
;     ...
;             for (int m = 0; m < 4; ++m) {
;                 const int row = row0 + ai * HALF + m * 16;
;                 const float rs = rsv[ai * 4 + m];
;                 const f32x4 g0 = acc[ai][0][m][0], g1 = acc[ai][0][m][1], u0 = acc[ai][1][m][0], u1 = acc[ai][1][m][1];
;                 const f32x2 o0 = swiglu_pk((f32x2){g0[0], g0[1]}, (f32x2){u0[0], u0[1]}, rs), o1 = swiglu_pk((f32x2){g0[2], g0[3]}, (f32x2){u0[2], u0[3]}, rs);
;                 const f32x2 o2 = swiglu_pk((f32x2){g1[0], g1[1]}, (f32x2){u1[0], u1[1]}, rs), o3 = swiglu_pk((f32x2){g1[2], g1[3]}, (f32x2){u1[2], u1[3]}, rs);
;                 u32x4 w; w.x = pk2(o0.x, o0.y); w.y = pk2(o1.x, o1.y); w.z = pk2(o2.x, o2.y); w.w = pk2(o3.x, o3.y);
;                 __builtin_nontemporal_store(w, (u32x4*)(G + (size_t)(row >> 8) * ((size_t)BM * FF) + (size_t)(col0 >> 6) * (BM * BK) + (size_t)(row & 255) * BK + (col0 & 63)));
;                 __builtin_amdgcn_sched_barrier(0);
	v_mul_f32_e32 v96, v106, v110
	v_mul_f32_e32 v97, v107, v111
	s_nop 0
	v_mul_f32_e32 v106, v98, v96
	v_mul_f32_e32 v107, v99, v97
	v_cvt_pk_bf16_f32 v96, v100, v101
	v_cvt_pk_bf16_f32 v97, v102, v103
	v_cvt_pk_bf16_f32 v98, v104, v105
	s_nop 0
	v_cvt_pk_bf16_f32 v99, v106, v107
	global_store_dwordx4 v[116:117], v[96:99], off offset:2048 nt
	v_mul_f32_e32 v92, v92, v152
	v_mul_f32_e32 v93, v93, v152
	v_mul_f32_e32 v94, v94, v152
	v_mul_f32_e32 v95, v95, v152
	v_mul_f32_e32 v96, s42, v92
	v_mul_f32_e32 v97, s42, v93
	v_mul_f32_e32 v98, s42, v94
	v_mul_f32_e32 v99, s42, v95
	v_exp_f32_e32 v96, v96
	v_exp_f32_e32 v97, v97
	v_exp_f32_e32 v98, v98
	v_exp_f32_e32 v99, v99
	v_mul_f32_e32 v84, v84, v152
	v_mul_f32_e32 v85, v85, v152
	v_add_f32_e32 v96, 1.0, v96
	v_add_f32_e32 v97, 1.0, v97
	v_mul_f32_e32 v86, v86, v152
	v_mul_f32_e32 v87, v87, v152
	v_rcp_f32_e32 v96, v96
	v_rcp_f32_e32 v97, v97
	v_add_f32_e32 v98, 1.0, v98
	v_add_f32_e32 v99, 1.0, v99
	v_mul_f32_e32 v88, v88, v152
	v_mul_f32_e32 v89, v89, v152
	v_rcp_f32_e32 v98, v98
	v_rcp_f32_e32 v99, v99
	v_mul_f32_e32 v92, v92, v96
	v_mul_f32_e32 v93, v93, v97
	v_mul_f32_e32 v90, v90, v152
	v_mul_f32_e32 v91, v91, v152
	v_mul_f32_e32 v84, v84, v92
	v_mul_f32_e32 v85, v85, v93
	v_mul_f32_e32 v92, v94, v98
	v_mul_f32_e32 v93, v95, v99
	v_mul_f32_e32 v94, s42, v90
	v_mul_f32_e32 v95, s42, v91
	v_mul_f32_e32 v86, v86, v92
	v_mul_f32_e32 v87, v87, v93
	v_mul_f32_e32 v92, s42, v88
	v_mul_f32_e32 v93, s42, v89
	v_exp_f32_e32 v94, v94
	v_exp_f32_e32 v92, v92
	v_exp_f32_e32 v93, v93
	v_exp_f32_e32 v95, v95
	v_mul_f32_e32 v80, v80, v152
	v_mul_f32_e32 v81, v81, v152
	v_mul_f32_e32 v82, v82, v152
	v_mul_f32_e32 v83, v83, v152
	v_add_f32_e32 v92, 1.0, v92
	v_add_f32_e32 v93, 1.0, v93
	v_add_f32_e32 v94, 1.0, v94
	v_add_f32_e32 v95, 1.0, v95
	v_rcp_f32_e32 v92, v92
	v_rcp_f32_e32 v93, v93
	v_rcp_f32_e32 v94, v94
	v_rcp_f32_e32 v95, v95
	v_mul_f32_e32 v88, v88, v92
	v_mul_f32_e32 v89, v89, v93
	s_nop 0
	v_mul_f32_e32 v88, v80, v88
	v_mul_f32_e32 v89, v81, v89
	v_mul_f32_e32 v80, v90, v94
	v_mul_f32_e32 v81, v91, v95
	s_nop 0
	v_mul_f32_e32 v90, v82, v80
	v_mul_f32_e32 v91, v83, v81
	v_cvt_pk_bf16_f32 v80, v84, v85
	v_add_co_u32_e32 v84, vcc, s61, v116
	v_cvt_pk_bf16_f32 v81, v86, v87
	v_cvt_pk_bf16_f32 v82, v88, v89
	v_cvt_pk_bf16_f32 v83, v90, v91
	s_nop 1
	v_addc_co_u32_e32 v85, vcc, 0, v117, vcc
	global_store_dwordx4 v[84:85], v[80:83], off nt
	v_mul_f32_e32 v76, v76, v150
	v_mul_f32_e32 v77, v77, v150
	v_mul_f32_e32 v78, v78, v150
	v_mul_f32_e32 v79, v79, v150
	v_mul_f32_e32 v80, s42, v76
	v_mul_f32_e32 v81, s42, v77
	v_mul_f32_e32 v82, s42, v78
	v_mul_f32_e32 v83, s42, v79
	v_exp_f32_e32 v80, v80
	v_exp_f32_e32 v81, v81
	v_exp_f32_e32 v82, v82
	v_exp_f32_e32 v83, v83
	v_mul_f32_e32 v68, v68, v150
	v_mul_f32_e32 v69, v69, v150
	v_add_f32_e32 v80, 1.0, v80
	v_add_f32_e32 v81, 1.0, v81
	v_mul_f32_e32 v70, v70, v150
	v_mul_f32_e32 v71, v71, v150
	v_rcp_f32_e32 v80, v80
	v_rcp_f32_e32 v81, v81
	v_add_f32_e32 v82, 1.0, v82
	v_add_f32_e32 v83, 1.0, v83
	v_mul_f32_e32 v72, v72, v150
	v_mul_f32_e32 v73, v73, v150
	v_rcp_f32_e32 v82, v82
	v_rcp_f32_e32 v83, v83
	v_mul_f32_e32 v76, v76, v80
	v_mul_f32_e32 v77, v77, v81
	v_mul_f32_e32 v74, v74, v150
	v_mul_f32_e32 v75, v75, v150
	v_mul_f32_e32 v68, v68, v76
	v_mul_f32_e32 v69, v69, v77
	v_mul_f32_e32 v76, v78, v82
	v_mul_f32_e32 v77, v79, v83
	v_mul_f32_e32 v78, s42, v74
	v_mul_f32_e32 v79, s42, v75
	v_mul_f32_e32 v70, v70, v76
	v_mul_f32_e32 v71, v71, v77
	v_mul_f32_e32 v76, s42, v72
	v_mul_f32_e32 v77, s42, v73
	v_exp_f32_e32 v78, v78
	v_exp_f32_e32 v76, v76
	v_exp_f32_e32 v77, v77
	v_exp_f32_e32 v79, v79
	v_mul_f32_e32 v64, v64, v150
	v_mul_f32_e32 v65, v65, v150
	v_mul_f32_e32 v66, v66, v150
	v_mul_f32_e32 v67, v67, v150
	v_add_f32_e32 v76, 1.0, v76
	v_add_f32_e32 v77, 1.0, v77
	v_add_f32_e32 v78, 1.0, v78
	v_add_f32_e32 v79, 1.0, v79
	v_rcp_f32_e32 v76, v76
	v_rcp_f32_e32 v77, v77
	v_rcp_f32_e32 v78, v78
	v_rcp_f32_e32 v79, v79
	v_mul_f32_e32 v72, v72, v76
	v_mul_f32_e32 v73, v73, v77
	s_nop 0
	v_mul_f32_e32 v72, v64, v72
	v_mul_f32_e32 v73, v65, v73
	v_mul_f32_e32 v64, v74, v78
	v_mul_f32_e32 v65, v75, v79
	s_nop 0
	v_mul_f32_e32 v74, v66, v64
	v_mul_f32_e32 v75, v67, v65
	v_cvt_pk_bf16_f32 v64, v68, v69
	v_cvt_pk_bf16_f32 v65, v70, v71
	v_cvt_pk_bf16_f32 v66, v72, v73
	s_nop 0
	v_cvt_pk_bf16_f32 v67, v74, v75
	global_store_dwordx4 v[84:85], v[64:67], off offset:2048 nt
	v_mul_f32_e32 v60, v60, v148
	v_mul_f32_e32 v61, v61, v148
	v_mul_f32_e32 v62, v62, v148
	v_mul_f32_e32 v63, v63, v148
	v_mul_f32_e32 v66, s42, v60
	v_mul_f32_e32 v67, s42, v61
	v_mul_f32_e32 v68, s42, v62
	v_mul_f32_e32 v69, s42, v63
	v_exp_f32_e32 v66, v66
	v_exp_f32_e32 v67, v67
	v_exp_f32_e32 v68, v68
	v_exp_f32_e32 v69, v69
	v_mul_f32_e32 v52, v52, v148
	v_mul_f32_e32 v53, v53, v148
	v_add_f32_e32 v66, 1.0, v66
	v_add_f32_e32 v67, 1.0, v67
	v_mul_f32_e32 v54, v54, v148
	v_mul_f32_e32 v55, v55, v148
	v_rcp_f32_e32 v66, v66
	v_rcp_f32_e32 v67, v67
	v_add_f32_e32 v68, 1.0, v68
	v_add_f32_e32 v69, 1.0, v69
	v_mul_f32_e32 v56, v56, v148
	v_mul_f32_e32 v57, v57, v148
	v_rcp_f32_e32 v68, v68
	v_rcp_f32_e32 v69, v69
	v_mul_f32_e32 v60, v60, v66
	v_mul_f32_e32 v61, v61, v67
	v_mul_f32_e32 v58, v58, v148
	v_mul_f32_e32 v59, v59, v148
	v_mul_f32_e32 v52, v52, v60
	v_mul_f32_e32 v53, v53, v61
	v_mul_f32_e32 v60, v62, v68
	v_mul_f32_e32 v61, v63, v69
	v_mul_f32_e32 v62, s42, v58
	v_mul_f32_e32 v63, s42, v59
	v_mul_f32_e32 v54, v54, v60
	v_mul_f32_e32 v55, v55, v61
	v_mul_f32_e32 v60, s42, v56
	v_mul_f32_e32 v61, s42, v57
	v_exp_f32_e32 v62, v62
	v_exp_f32_e32 v60, v60
	v_exp_f32_e32 v61, v61
; __device__ __forceinline__ unsigned pk2(float lo, float hi) { unsigned r; asm volatile("v_cvt_pk_bf16_f32 %0, %1, %2" : "=v"(r) : "v"(lo), "v"(hi)); return r; }
; __device__ __forceinline__ f32x2 swiglu_pk(f32x2 g, f32x2 u, float rs) {
;     const f32x2 t = g * rs, s = t * (-1.44269504089f);
;     f32x2 e; e.x = __builtin_amdgcn_exp2f(s.x); e.y = __builtin_amdgcn_exp2f(s.y);
;     const f32x2 d = e + 1.0f; f32x2 r; r.x = __builtin_amdgcn_rcpf(d.x); r.y = __builtin_amdgcn_rcpf(d.y);
;     return (t * r) * (u * rs);
; }
;     __device__ __forceinline__ void operator()(const f32x4 (&acc)[2][2][4][2], const Unit& u, int wr, int wc, int fr, int fq) const {
;     ...
;             for (int m = 0; m < 4; ++m) {
;                 const int row = row0 + ai * HALF + m * 16;
;                 const float rs = rsv[ai * 4 + m];
;                 const f32x4 g0 = acc[ai][0][m][0], g1 = acc[ai][0][m][1], u0 = acc[ai][1][m][0], u1 = acc[ai][1][m][1];
;                 const f32x2 o0 = swiglu_pk((f32x2){g0[0], g0[1]}, (f32x2){u0[0], u0[1]}, rs), o1 = swiglu_pk((f32x2){g0[2], g0[3]}, (f32x2){u0[2], u0[3]}, rs);
;                 const f32x2 o2 = swiglu_pk((f32x2){g1[0], g1[1]}, (f32x2){u1[0], u1[1]}, rs), o3 = swiglu_pk((f32x2){g1[2], g1[3]}, (f32x2){u1[2], u1[3]}, rs);
;                 u32x4 w; w.x = pk2(o0.x, o0.y); w.y = pk2(o1.x, o1.y); w.z = pk2(o2.x, o2.y); w.w = pk2(o3.x, o3.y);
;                 __builtin_nontemporal_store(w, (u32x4*)(G + (size_t)(row >> 8) * ((size_t)BM * FF) + (size_t)(col0 >> 6) * (BM * BK) + (size_t)(row & 255) * BK + (col0 & 63)));
;                 __builtin_amdgcn_sched_barrier(0);
	v_exp_f32_e32 v63, v63
	v_lshrrev_b32_e32 v64, 8, v151
	v_mul_f32_e32 v48, v48, v148
	v_mul_f32_e32 v49, v49, v148
	v_add_f32_e32 v60, 1.0, v60
	v_add_f32_e32 v61, 1.0, v61
	v_add_f32_e32 v62, 1.0, v62
	v_add_f32_e32 v63, 1.0, v63
	v_rcp_f32_e32 v60, v60
	v_rcp_f32_e32 v61, v61
	v_rcp_f32_e32 v62, v62
	v_rcp_f32_e32 v63, v63
	v_mul_hi_i32_i24_e32 v65, 0x2c0000, v64
	v_mul_f32_e32 v56, v56, v60
	v_mul_f32_e32 v57, v57, v61
	v_mul_i32_i24_e32 v64, 0x2c0000, v64
	v_mul_f32_e32 v56, v48, v56
	v_mul_f32_e32 v57, v49, v57
	v_mul_f32_e32 v48, v58, v62
	v_mul_f32_e32 v49, v59, v63
	v_mul_f32_e32 v50, v50, v148
	v_mul_f32_e32 v51, v51, v148
	s_nop 0
	v_mul_f32_e32 v58, v50, v48
	v_mul_f32_e32 v59, v51, v49
	v_cvt_pk_bf16_f32 v48, v52, v53
	v_cvt_pk_bf16_f32 v49, v54, v55
	v_lshl_add_u64 v[52:53], s[36:37], 0, v[64:65]
	v_lshlrev_b32_e32 v54, 7, v151
	v_lshl_add_u64 v[52:53], v[52:53], 0, s[10:11]
	v_and_b32_e32 v132, 0x6780, v54
	v_lshl_add_u64 v[52:53], v[52:53], 0, v[132:133]
	v_lshl_add_u64 v[52:53], v[52:53], 0, v[140:141]
	v_cvt_pk_bf16_f32 v50, v56, v57
	v_cvt_pk_bf16_f32 v51, v58, v59
	global_store_dwordx4 v[52:53], v[48:51], off nt
	v_mul_f32_e32 v44, v44, v146
	v_mul_f32_e32 v45, v45, v146
	v_mul_f32_e32 v46, v46, v146
	v_mul_f32_e32 v47, v47, v146
	v_mul_f32_e32 v48, s42, v44
	v_mul_f32_e32 v49, s42, v45
	v_mul_f32_e32 v50, s42, v46
	v_mul_f32_e32 v51, s42, v47
	v_exp_f32_e32 v48, v48
	v_exp_f32_e32 v49, v49
	v_exp_f32_e32 v50, v50
	v_exp_f32_e32 v51, v51
	v_mul_f32_e32 v36, v36, v146
	v_mul_f32_e32 v37, v37, v146
	v_add_f32_e32 v48, 1.0, v48
	v_add_f32_e32 v49, 1.0, v49
	v_mul_f32_e32 v38, v38, v146
	v_mul_f32_e32 v39, v39, v146
	v_rcp_f32_e32 v48, v48
	v_rcp_f32_e32 v49, v49
	v_add_f32_e32 v50, 1.0, v50
	v_add_f32_e32 v51, 1.0, v51
	v_mul_f32_e32 v40, v40, v146
	v_mul_f32_e32 v41, v41, v146
	v_rcp_f32_e32 v50, v50
	v_rcp_f32_e32 v51, v51
	v_mul_f32_e32 v44, v44, v48
	v_mul_f32_e32 v45, v45, v49
	v_mul_f32_e32 v42, v42, v146
	v_mul_f32_e32 v43, v43, v146
	v_mul_f32_e32 v36, v36, v44
	v_mul_f32_e32 v37, v37, v45
	v_mul_f32_e32 v44, v46, v50
	v_mul_f32_e32 v45, v47, v51
	v_mul_f32_e32 v46, s42, v42
	v_mul_f32_e32 v47, s42, v43
	v_mul_f32_e32 v38, v38, v44
	v_mul_f32_e32 v39, v39, v45
	v_mul_f32_e32 v44, s42, v40
	v_mul_f32_e32 v45, s42, v41
	v_exp_f32_e32 v46, v46
	v_exp_f32_e32 v44, v44
	v_exp_f32_e32 v45, v45
	v_exp_f32_e32 v47, v47
	v_mul_f32_e32 v32, v32, v146
	v_mul_f32_e32 v33, v33, v146
	v_mul_f32_e32 v34, v34, v146
	v_mul_f32_e32 v35, v35, v146
	v_add_f32_e32 v44, 1.0, v44
	v_add_f32_e32 v45, 1.0, v45
	v_add_f32_e32 v46, 1.0, v46
	v_add_f32_e32 v47, 1.0, v47
	v_rcp_f32_e32 v44, v44
	v_rcp_f32_e32 v45, v45
	v_rcp_f32_e32 v46, v46
	v_rcp_f32_e32 v47, v47
	v_mul_f32_e32 v40, v40, v44
	v_mul_f32_e32 v41, v41, v45
	s_nop 0
	v_mul_f32_e32 v40, v32, v40
	v_mul_f32_e32 v41, v33, v41
	v_mul_f32_e32 v32, v42, v46
	v_mul_f32_e32 v33, v43, v47
	s_nop 0
	v_mul_f32_e32 v42, v34, v32
	v_mul_f32_e32 v43, v35, v33
	v_cvt_pk_bf16_f32 v32, v36, v37
	v_cvt_pk_bf16_f32 v33, v38, v39
	v_cvt_pk_bf16_f32 v34, v40, v41
	s_nop 0
	v_cvt_pk_bf16_f32 v35, v42, v43
	global_store_dwordx4 v[52:53], v[32:35], off offset:2048 nt
	v_mul_f32_e32 v28, v28, v144
	v_mul_f32_e32 v29, v29, v144
	v_mul_f32_e32 v30, v30, v144
	v_mul_f32_e32 v31, v31, v144
	v_mul_f32_e32 v32, s42, v28
	v_mul_f32_e32 v33, s42, v29
	v_mul_f32_e32 v34, s42, v30
	v_mul_f32_e32 v35, s42, v31
	v_exp_f32_e32 v32, v32
	v_exp_f32_e32 v33, v33
	v_exp_f32_e32 v34, v34
	v_exp_f32_e32 v35, v35
	v_mul_f32_e32 v20, v20, v144
	v_mul_f32_e32 v21, v21, v144
	v_add_f32_e32 v32, 1.0, v32
	v_add_f32_e32 v33, 1.0, v33
	v_mul_f32_e32 v22, v22, v144
	v_mul_f32_e32 v23, v23, v144
; __device__ __forceinline__ unsigned pk2(float lo, float hi) { unsigned r; asm volatile("v_cvt_pk_bf16_f32 %0, %1, %2" : "=v"(r) : "v"(lo), "v"(hi)); return r; }
; #define PG8_BAR __builtin_amdgcn_s_barrier()
; template <class Epi>
; __device__ __forceinline__ void gemm_phase(LAS unsigned char* lds, const Gemm g, const StaticOrder& S, const Epi& E) {
;     ...
;         if (wr == 0) PG8_BAR;
;         E(acc, cur, wr, wc, fr, fq);
;         if (!has_next) break;
; #pragma unroll
;         for (int a = 0; a < 2; ++a)
; #pragma unroll
;             for (int b = 0; b < 2; ++b)
; #pragma unroll
;                 for (int m = 0; m < 4; ++m)
; #pragma unroll
;                     for (int n = 0; n < 2; ++n) acc[a][b][m][n] = (f32x4){0.f, 0.f, 0.f, 0.f};
;         cur = nxt; cA = nA; cB = nB; ++ui;
;         if (wr == 1) PG8_BAR;
;     }
;     __device__ __forceinline__ void operator()(const f32x4 (&acc)[2][2][4][2], const Unit& u, int wr, int wc, int fr, int fq) const {
;     ...
;             for (int m = 0; m < 4; ++m) {
;                 const int row = row0 + ai * HALF + m * 16;
;                 const float rs = rsv[ai * 4 + m];
;                 const f32x4 g0 = acc[ai][0][m][0], g1 = acc[ai][0][m][1], u0 = acc[ai][1][m][0], u1 = acc[ai][1][m][1];
;                 const f32x2 o0 = swiglu_pk((f32x2){g0[0], g0[1]}, (f32x2){u0[0], u0[1]}, rs), o1 = swiglu_pk((f32x2){g0[2], g0[3]}, (f32x2){u0[2], u0[3]}, rs);
;                 const f32x2 o2 = swiglu_pk((f32x2){g1[0], g1[1]}, (f32x2){u1[0], u1[1]}, rs), o3 = swiglu_pk((f32x2){g1[2], g1[3]}, (f32x2){u1[2], u1[3]}, rs);
;                 u32x4 w; w.x = pk2(o0.x, o0.y); w.y = pk2(o1.x, o1.y); w.z = pk2(o2.x, o2.y); w.w = pk2(o3.x, o3.y);
;                 __builtin_nontemporal_store(w, (u32x4*)(G + (size_t)(row >> 8) * ((size_t)BM * FF) + (size_t)(col0 >> 6) * (BM * BK) + (size_t)(row & 255) * BK + (col0 & 63)));
;                 __builtin_amdgcn_sched_barrier(0);
;             }
	v_rcp_f32_e32 v32, v32
	v_rcp_f32_e32 v33, v33
	v_add_f32_e32 v34, 1.0, v34
	v_add_f32_e32 v35, 1.0, v35
	v_mul_f32_e32 v24, v24, v144
	v_mul_f32_e32 v25, v25, v144
	v_rcp_f32_e32 v34, v34
	v_rcp_f32_e32 v35, v35
	v_mul_f32_e32 v28, v28, v32
	v_mul_f32_e32 v29, v29, v33
	v_mul_f32_e32 v26, v26, v144
	v_mul_f32_e32 v27, v27, v144
	v_mul_f32_e32 v20, v20, v28
	v_mul_f32_e32 v21, v21, v29
	v_mul_f32_e32 v28, v30, v34
	v_mul_f32_e32 v29, v31, v35
	v_mul_f32_e32 v30, s42, v26
	v_mul_f32_e32 v31, s42, v27
	v_mul_f32_e32 v22, v22, v28
	v_mul_f32_e32 v23, v23, v29
	v_mul_f32_e32 v28, s42, v24
	v_mul_f32_e32 v29, s42, v25
	v_exp_f32_e32 v30, v30
	v_exp_f32_e32 v28, v28
	v_exp_f32_e32 v29, v29
	v_exp_f32_e32 v31, v31
	v_mul_f32_e32 v16, v16, v144
	v_mul_f32_e32 v17, v17, v144
	v_mul_f32_e32 v18, v18, v144
	v_mul_f32_e32 v19, v19, v144
	v_add_f32_e32 v28, 1.0, v28
	v_add_f32_e32 v29, 1.0, v29
	v_add_f32_e32 v30, 1.0, v30
	v_add_f32_e32 v31, 1.0, v31
	v_rcp_f32_e32 v28, v28
	v_rcp_f32_e32 v29, v29
	v_rcp_f32_e32 v30, v30
	v_rcp_f32_e32 v31, v31
	v_mul_f32_e32 v24, v24, v28
	v_mul_f32_e32 v25, v25, v29
	s_nop 0
	v_mul_f32_e32 v24, v16, v24
	v_mul_f32_e32 v25, v17, v25
	v_mul_f32_e32 v16, v26, v30
	v_mul_f32_e32 v17, v27, v31
	s_nop 0
	v_mul_f32_e32 v26, v18, v16
	v_mul_f32_e32 v27, v19, v17
	v_cvt_pk_bf16_f32 v16, v20, v21
	v_add_co_u32_e32 v20, vcc, s61, v52
	v_cvt_pk_bf16_f32 v17, v22, v23
	v_cvt_pk_bf16_f32 v18, v24, v25
	v_cvt_pk_bf16_f32 v19, v26, v27
	s_nop 1
	v_addc_co_u32_e32 v21, vcc, 0, v53, vcc
	global_store_dwordx4 v[20:21], v[16:19], off nt
	v_mul_f32_e32 v12, v12, v142
	v_mul_f32_e32 v13, v13, v142
	v_mul_f32_e32 v14, v14, v142
	v_mul_f32_e32 v15, v15, v142
	v_mul_f32_e32 v16, s42, v12
	v_mul_f32_e32 v17, s42, v13
	v_mul_f32_e32 v18, s42, v14
	v_mul_f32_e32 v19, s42, v15
	v_exp_f32_e32 v16, v16
	v_exp_f32_e32 v17, v17
	v_exp_f32_e32 v18, v18
	v_exp_f32_e32 v19, v19
	v_mul_f32_e32 v4, v4, v142
	v_mul_f32_e32 v5, v5, v142
	v_add_f32_e32 v16, 1.0, v16
	v_add_f32_e32 v17, 1.0, v17
	v_mul_f32_e32 v6, v6, v142
	v_mul_f32_e32 v7, v7, v142
	v_rcp_f32_e32 v16, v16
	v_rcp_f32_e32 v17, v17
	v_add_f32_e32 v18, 1.0, v18
	v_add_f32_e32 v19, 1.0, v19
	v_mul_f32_e32 v8, v8, v142
	v_mul_f32_e32 v9, v9, v142
	v_rcp_f32_e32 v18, v18
	v_rcp_f32_e32 v19, v19
	v_mul_f32_e32 v12, v12, v16
	v_mul_f32_e32 v13, v13, v17
	v_mul_f32_e32 v10, v10, v142
	v_mul_f32_e32 v11, v11, v142
	v_mul_f32_e32 v4, v4, v12
	v_mul_f32_e32 v5, v5, v13
	v_mul_f32_e32 v12, v14, v18
	v_mul_f32_e32 v13, v15, v19
	v_mul_f32_e32 v14, s42, v10
	v_mul_f32_e32 v15, s42, v11
	v_mul_f32_e32 v6, v6, v12
	v_mul_f32_e32 v7, v7, v13
	v_mul_f32_e32 v12, s42, v8
	v_mul_f32_e32 v13, s42, v9
	v_exp_f32_e32 v14, v14
	v_exp_f32_e32 v12, v12
	v_exp_f32_e32 v13, v13
	v_exp_f32_e32 v15, v15
	v_mul_f32_e32 v0, v0, v142
	v_mul_f32_e32 v1, v1, v142
	v_mul_f32_e32 v2, v2, v142
	v_mul_f32_e32 v3, v3, v142
	v_add_f32_e32 v12, 1.0, v12
	v_add_f32_e32 v13, 1.0, v13
	v_add_f32_e32 v14, 1.0, v14
	v_add_f32_e32 v15, 1.0, v15
	v_rcp_f32_e32 v12, v12
	v_rcp_f32_e32 v13, v13
	v_rcp_f32_e32 v14, v14
	v_rcp_f32_e32 v15, v15
	v_mul_f32_e32 v8, v8, v12
	v_mul_f32_e32 v9, v9, v13
	s_nop 0
	v_mul_f32_e32 v8, v0, v8
	v_mul_f32_e32 v9, v1, v9
	v_mul_f32_e32 v0, v10, v14
	v_mul_f32_e32 v1, v11, v15
	s_nop 0
	v_mul_f32_e32 v10, v2, v0
	v_mul_f32_e32 v11, v3, v1
	v_cvt_pk_bf16_f32 v0, v4, v5
	v_cvt_pk_bf16_f32 v1, v6, v7
	v_cvt_pk_bf16_f32 v2, v8, v9
	s_nop 0
	v_cvt_pk_bf16_f32 v3, v10, v11
	global_store_dwordx4 v[20:21], v[0:3], off offset:2048 nt
	s_and_b64 vcc, exec, s[8:9]
	s_mov_b64 s[8:9], -1
	s_cbranch_vccnz .LBB0_1201
	s_andn2_b64 vcc, exec, s[34:35]
	s_cbranch_vccnz .LBB0_1200
	s_barrier
	s_branch .LBB0_1200
